# kt_tile: the 8 tile loads issued together with counted waits; 8 bias loads hoisted and per-store vmcnt(0) removed
# speedup vs baseline: 1.0133x; 1.0065x over previous
.LBB0_564:
	s_waitcnt vmcnt(0)
	v_mov_b32_e32 v34, v208
	s_lshl_b32 s8, s13, 3
	s_and_b32 s8, s8, 0xffffff80
	s_load_dwordx2 s[14:15], s[0:1], 0x80
	v_and_b32_e32 v84, 15, v34
	v_ashrrev_i32_e32 v85, 4, v34
	v_lshlrev_b32_e32 v0, 4, v84
	v_lshl_add_u64 v[6:7], s[6:7], 0, v[0:1]
	v_add_u32_e32 v2, s8, v85
	v_mov_b32_e32 v3, 0
	v_lshlrev_b64 v[2:3], 8, v[2:3]
	v_lshl_add_u64 v[2:3], v[6:7], 0, v[2:3]
	global_load_dwordx4 v[52:55], v[2:3], off
	v_add_co_u32_e32 v2, vcc, 0x2000, v2
	s_nop 1
	v_addc_co_u32_e32 v3, vcc, 0, v3, vcc
	global_load_dwordx4 v[56:59], v[2:3], off
	v_add_co_u32_e32 v2, vcc, 0x2000, v2
	s_nop 1
	v_addc_co_u32_e32 v3, vcc, 0, v3, vcc
	global_load_dwordx4 v[60:63], v[2:3], off
	v_add_co_u32_e32 v2, vcc, 0x2000, v2
	s_nop 1
	v_addc_co_u32_e32 v3, vcc, 0, v3, vcc
	global_load_dwordx4 v[64:67], v[2:3], off
	s_lshl_b32 s9, s13, 7
	s_and_b32 s9, s9, 0x780
	v_and_b32_e32 v86, 31, v34
	v_lshlrev_b32_e32 v0, 4, v86
	s_waitcnt lgkmcnt(0)
	s_add_u32 s14, s14, s2
	s_addc_u32 s15, s15, s3
	s_lshl_b32 s16, s9, 2
	s_add_u32 s14, s14, s16
	s_addc_u32 s15, s15, 0
	v_lshl_add_u64 v[8:9], s[14:15], 0, v[0:1]
	v_ashrrev_i32_e32 v2, 5, v34
	v_mov_b32_e32 v3, 0
	v_lshlrev_b64 v[2:3], 13, v[2:3]
	v_lshl_add_u64 v[2:3], v[8:9], 0, v[2:3]
	global_load_dwordx4 v[68:71], v[2:3], off
	v_add_co_u32_e32 v2, vcc, 0x20000, v2
	s_nop 1
	v_addc_co_u32_e32 v3, vcc, 0, v3, vcc
	global_load_dwordx4 v[72:75], v[2:3], off
	v_add_co_u32_e32 v2, vcc, 0x20000, v2
	s_nop 1
	v_addc_co_u32_e32 v3, vcc, 0, v3, vcc
	global_load_dwordx4 v[76:79], v[2:3], off
	v_add_co_u32_e32 v2, vcc, 0x20000, v2
	s_nop 1
	v_addc_co_u32_e32 v3, vcc, 0, v3, vcc
	global_load_dwordx4 v[80:83], v[2:3], off
	v_mul_u32_u24_e32 v87, 0x840, v84
	v_lshl_add_u32 v87, v85, 2, v87
	v_add_u32_e32 v88, 0x400, v87
	v_ashrrev_i32_e32 v89, 5, v34
	v_lshlrev_b32_e32 v89, 9, v89
	v_lshl_add_u32 v89, v86, 4, v89
	s_waitcnt vmcnt(7)
	ds_write2_b32 v87, v52, v53 offset0:0 offset1:132
	ds_write2_b32 v88, v54, v55 offset0:8 offset1:140
	s_waitcnt vmcnt(6)
	ds_write2_b32 v87, v56, v57 offset0:32 offset1:164
	ds_write2_b32 v88, v58, v59 offset0:40 offset1:172
	s_waitcnt vmcnt(5)
	ds_write2_b32 v87, v60, v61 offset0:64 offset1:196
	ds_write2_b32 v88, v62, v63 offset0:72 offset1:204
	s_waitcnt vmcnt(4)
	ds_write2_b32 v87, v64, v65 offset0:96 offset1:228
	ds_write2_b32 v88, v66, v67 offset0:104 offset1:236
	s_waitcnt vmcnt(3)
	ds_write_b128 v89, v[68:71] offset:34816
	s_waitcnt vmcnt(2)
	ds_write_b128 v89, v[72:75] offset:43008
	s_waitcnt vmcnt(1)
	ds_write_b128 v89, v[76:79] offset:51200
	s_waitcnt vmcnt(0)
	ds_write_b128 v89, v[80:83] offset:59392
	s_add_i32 s14, 0, 0x8800
	v_and_b32_e32 v2, 0xffffffe0, v34
	v_and_b32_e32 v0, 31, v34
	v_add_u32_e32 v36, s14, v2
	v_mov_b32_e32 v2, 0
	v_lshl_add_u32 v35, v0, 4, 0
	s_mov_b32 s14, 0
	v_mov_b32_e32 v3, v2
	v_mov_b32_e32 v4, v2
	v_mov_b32_e32 v5, v2
	v_mov_b32_e32 v30, v2
	v_mov_b32_e32 v31, v2
	v_mov_b32_e32 v32, v2
	v_mov_b32_e32 v33, v2
	v_mov_b32_e32 v26, v2
	v_mov_b32_e32 v27, v2
	v_mov_b32_e32 v28, v2
	v_mov_b32_e32 v29, v2
	v_mov_b32_e32 v22, v2
	v_mov_b32_e32 v23, v2
	v_mov_b32_e32 v24, v2
	v_mov_b32_e32 v25, v2
	v_mov_b32_e32 v18, v2
	v_mov_b32_e32 v19, v2
	v_mov_b32_e32 v20, v2
	v_mov_b32_e32 v21, v2
	v_mov_b32_e32 v14, v2
	v_mov_b32_e32 v15, v2
	v_mov_b32_e32 v16, v2
	v_mov_b32_e32 v17, v2
	v_mov_b32_e32 v10, v2
	v_mov_b32_e32 v11, v2
	v_mov_b32_e32 v12, v2
	v_mov_b32_e32 v13, v2
	v_mov_b32_e32 v6, v2
	v_mov_b32_e32 v7, v2
	v_mov_b32_e32 v8, v2
	v_mov_b32_e32 v9, v2
	s_waitcnt lgkmcnt(0)
	s_barrier
.LBB0_565:
	v_add_u32_e32 v37, s14, v36
	ds_read_b128 v[38:41], v35
	ds_read_b128 v[42:45], v37
	ds_read_b128 v[46:49], v37 offset:16
	s_addk_i32 s14, 0x800
	s_cmpk_lg_u32 s14, 0x8000
	s_waitcnt lgkmcnt(1)
	v_pk_fma_f32 v[32:33], v[40:41], v[42:43], v[32:33] op_sel_hi:[1,0,1]
	v_pk_fma_f32 v[30:31], v[38:39], v[42:43], v[30:31] op_sel_hi:[1,0,1]
	v_pk_fma_f32 v[28:29], v[40:41], v[42:43], v[28:29] op_sel:[0,1,0]
	v_pk_fma_f32 v[26:27], v[38:39], v[42:43], v[26:27] op_sel:[0,1,0]
	v_mov_b32_e32 v42, v45
	s_waitcnt lgkmcnt(0)
	v_pk_fma_f32 v[50:51], v[38:39], v[48:49], v[6:7] op_sel_hi:[1,0,1]
	v_mov_b32_e32 v6, v49
	v_pk_fma_f32 v[24:25], v[40:41], v[44:45], v[24:25] op_sel_hi:[1,0,1]
	v_pk_fma_f32 v[22:23], v[38:39], v[44:45], v[22:23] op_sel_hi:[1,0,1]
	v_pk_fma_f32 v[20:21], v[40:41], v[42:43], v[20:21] op_sel_hi:[1,0,1]
	v_pk_fma_f32 v[18:19], v[38:39], v[42:43], v[18:19] op_sel_hi:[1,0,1]
	v_pk_fma_f32 v[16:17], v[40:41], v[46:47], v[16:17] op_sel_hi:[1,0,1]
	v_pk_fma_f32 v[14:15], v[38:39], v[46:47], v[14:15] op_sel_hi:[1,0,1]
	v_pk_fma_f32 v[42:43], v[40:41], v[46:47], v[12:13] op_sel:[0,1,0]
	v_pk_fma_f32 v[44:45], v[38:39], v[46:47], v[10:11] op_sel:[0,1,0]
	v_pk_fma_f32 v[46:47], v[40:41], v[48:49], v[8:9] op_sel_hi:[1,0,1]
	v_pk_fma_f32 v[40:41], v[40:41], v[6:7], v[4:5] op_sel_hi:[1,0,1]
	v_pk_fma_f32 v[38:39], v[38:39], v[6:7], v[2:3] op_sel_hi:[1,0,1]
	ds_read_b128 v[2:5], v35 offset:528
	ds_read_b128 v[6:9], v37 offset:512
	ds_read_b128 v[10:13], v37 offset:528
	s_waitcnt lgkmcnt(1)
	v_pk_fma_f32 v[32:33], v[4:5], v[6:7], v[32:33] op_sel_hi:[1,0,1]
	v_pk_fma_f32 v[30:31], v[2:3], v[6:7], v[30:31] op_sel_hi:[1,0,1]
	v_pk_fma_f32 v[28:29], v[4:5], v[6:7], v[28:29] op_sel:[0,1,0]
	v_pk_fma_f32 v[26:27], v[2:3], v[6:7], v[26:27] op_sel:[0,1,0]
	v_mov_b32_e32 v6, v9
	v_pk_fma_f32 v[20:21], v[4:5], v[6:7], v[20:21] op_sel_hi:[1,0,1]
	v_pk_fma_f32 v[18:19], v[2:3], v[6:7], v[18:19] op_sel_hi:[1,0,1]
	s_waitcnt lgkmcnt(0)
	v_mov_b32_e32 v6, v13
	v_pk_fma_f32 v[24:25], v[4:5], v[8:9], v[24:25] op_sel_hi:[1,0,1]
	v_pk_fma_f32 v[22:23], v[2:3], v[8:9], v[22:23] op_sel_hi:[1,0,1]
	v_pk_fma_f32 v[16:17], v[4:5], v[10:11], v[16:17] op_sel_hi:[1,0,1]
	v_pk_fma_f32 v[14:15], v[2:3], v[10:11], v[14:15] op_sel_hi:[1,0,1]
	v_pk_fma_f32 v[42:43], v[4:5], v[10:11], v[42:43] op_sel:[0,1,0]
	v_pk_fma_f32 v[44:45], v[2:3], v[10:11], v[44:45] op_sel:[0,1,0]
	v_pk_fma_f32 v[46:47], v[4:5], v[12:13], v[46:47] op_sel_hi:[1,0,1]
	v_pk_fma_f32 v[48:49], v[2:3], v[12:13], v[50:51] op_sel_hi:[1,0,1]
	v_pk_fma_f32 v[40:41], v[4:5], v[6:7], v[40:41] op_sel_hi:[1,0,1]
	v_pk_fma_f32 v[38:39], v[2:3], v[6:7], v[38:39] op_sel_hi:[1,0,1]
	ds_read_b128 v[2:5], v35 offset:1056
	ds_read_b128 v[6:9], v37 offset:1024
	ds_read_b128 v[10:13], v37 offset:1040
	s_waitcnt lgkmcnt(1)
	v_pk_fma_f32 v[32:33], v[4:5], v[6:7], v[32:33] op_sel_hi:[1,0,1]
	v_pk_fma_f32 v[30:31], v[2:3], v[6:7], v[30:31] op_sel_hi:[1,0,1]
	v_pk_fma_f32 v[28:29], v[4:5], v[6:7], v[28:29] op_sel:[0,1,0]
	v_pk_fma_f32 v[26:27], v[2:3], v[6:7], v[26:27] op_sel:[0,1,0]
	v_mov_b32_e32 v6, v9
	v_pk_fma_f32 v[20:21], v[4:5], v[6:7], v[20:21] op_sel_hi:[1,0,1]
	v_pk_fma_f32 v[18:19], v[2:3], v[6:7], v[18:19] op_sel_hi:[1,0,1]
	s_waitcnt lgkmcnt(0)
	v_mov_b32_e32 v6, v13
	v_pk_fma_f32 v[24:25], v[4:5], v[8:9], v[24:25] op_sel_hi:[1,0,1]
	v_pk_fma_f32 v[22:23], v[2:3], v[8:9], v[22:23] op_sel_hi:[1,0,1]
	v_pk_fma_f32 v[16:17], v[4:5], v[10:11], v[16:17] op_sel_hi:[1,0,1]
	v_pk_fma_f32 v[14:15], v[2:3], v[10:11], v[14:15] op_sel_hi:[1,0,1]
	v_pk_fma_f32 v[42:43], v[4:5], v[10:11], v[42:43] op_sel:[0,1,0]
	v_pk_fma_f32 v[10:11], v[2:3], v[10:11], v[44:45] op_sel:[0,1,0]
	v_pk_fma_f32 v[44:45], v[4:5], v[12:13], v[46:47] op_sel_hi:[1,0,1]
	v_pk_fma_f32 v[46:47], v[2:3], v[12:13], v[48:49] op_sel_hi:[1,0,1]
	v_pk_fma_f32 v[48:49], v[4:5], v[6:7], v[40:41] op_sel_hi:[1,0,1]
	v_pk_fma_f32 v[50:51], v[2:3], v[6:7], v[38:39] op_sel_hi:[1,0,1]
	ds_read_b128 v[2:5], v35 offset:1584
	ds_read_b128 v[6:9], v37 offset:1536
	ds_read_b128 v[38:41], v37 offset:1552
	v_add_u32_e32 v35, 0x840, v35
	s_waitcnt lgkmcnt(1)
	v_pk_fma_f32 v[32:33], v[4:5], v[6:7], v[32:33] op_sel_hi:[1,0,1]
	v_pk_fma_f32 v[30:31], v[2:3], v[6:7], v[30:31] op_sel_hi:[1,0,1]
	v_pk_fma_f32 v[28:29], v[4:5], v[6:7], v[28:29] op_sel:[0,1,0]
	v_pk_fma_f32 v[26:27], v[2:3], v[6:7], v[26:27] op_sel:[0,1,0]
	v_mov_b32_e32 v6, v9
	s_waitcnt lgkmcnt(0)
	v_pk_fma_f32 v[16:17], v[4:5], v[38:39], v[16:17] op_sel_hi:[1,0,1]
	v_pk_fma_f32 v[14:15], v[2:3], v[38:39], v[14:15] op_sel_hi:[1,0,1]
	v_pk_fma_f32 v[12:13], v[4:5], v[38:39], v[42:43] op_sel:[0,1,0]
	v_pk_fma_f32 v[10:11], v[2:3], v[38:39], v[10:11] op_sel:[0,1,0]
	v_mov_b32_e32 v38, v41
	v_pk_fma_f32 v[24:25], v[4:5], v[8:9], v[24:25] op_sel_hi:[1,0,1]
	v_pk_fma_f32 v[22:23], v[2:3], v[8:9], v[22:23] op_sel_hi:[1,0,1]
	v_pk_fma_f32 v[20:21], v[4:5], v[6:7], v[20:21] op_sel_hi:[1,0,1]
	v_pk_fma_f32 v[18:19], v[2:3], v[6:7], v[18:19] op_sel_hi:[1,0,1]
	v_pk_fma_f32 v[8:9], v[4:5], v[40:41], v[44:45] op_sel_hi:[1,0,1]
	v_pk_fma_f32 v[6:7], v[2:3], v[40:41], v[46:47] op_sel_hi:[1,0,1]
	v_pk_fma_f32 v[4:5], v[4:5], v[38:39], v[48:49] op_sel_hi:[1,0,1]
	v_pk_fma_f32 v[2:3], v[2:3], v[38:39], v[50:51] op_sel_hi:[1,0,1]
	s_cbranch_scc1 .LBB0_565
	v_ashrrev_i32_e32 v34, 2, v34
	s_load_dwordx2 s[14:15], s[0:1], 0x88
	v_and_b32_e32 v34, -8, v34
	v_add_u32_e32 v37, s9, v34
	v_add_u32_e32 v34, s10, v37
	v_ashrrev_i32_e32 v35, 31, v34
	s_waitcnt lgkmcnt(0)
	v_lshl_add_u64 v[34:35], v[34:35], 2, s[14:15]
	global_load_dword v36, v[34:35], off
	global_load_dword v52, v[34:35], off offset:4
	global_load_dword v54, v[34:35], off offset:8
	global_load_dword v56, v[34:35], off offset:12
	global_load_dword v58, v[34:35], off offset:16
	global_load_dword v60, v[34:35], off offset:20
	global_load_dword v62, v[34:35], off offset:24
	global_load_dword v64, v[34:35], off offset:28
	s_ashr_i32 s9, s8, 31
	s_lshl_b64 s[8:9], s[8:9], 2
	s_add_u32 s8, s11, s8
	v_lshlrev_b32_e32 v0, 4, v0
	s_addc_u32 s9, s12, s9
	v_lshl_add_u64 v[38:39], s[8:9], 0, v[0:1]
	v_mad_i64_i32 v[40:41], s[8:9], v37, s61, v[38:39]
	s_add_i32 s13, s13, s56
	s_cmpk_gt_i32 s13, 0x21f
	s_waitcnt vmcnt(0)
	v_pk_add_f32 v[32:33], v[32:33], v[36:37] op_sel_hi:[1,0]
	v_pk_add_f32 v[30:31], v[30:31], v[36:37] op_sel_hi:[1,0]
	global_store_dwordx4 v[40:41], v[30:33], off
	s_nop 1
	v_pk_add_f32 v[28:29], v[28:29], v[52:53] op_sel_hi:[1,0]
	v_or_b32_e32 v30, 1, v37
	v_mad_i64_i32 v[30:31], s[8:9], v30, s61, v[38:39]
	v_pk_add_f32 v[26:27], v[26:27], v[52:53] op_sel_hi:[1,0]
	global_store_dwordx4 v[30:31], v[26:29], off
	s_nop 1
	v_pk_add_f32 v[24:25], v[24:25], v[54:55] op_sel_hi:[1,0]
	v_or_b32_e32 v26, 2, v37
	v_mad_i64_i32 v[26:27], s[8:9], v26, s61, v[38:39]
	v_pk_add_f32 v[22:23], v[22:23], v[54:55] op_sel_hi:[1,0]
	global_store_dwordx4 v[26:27], v[22:25], off
	s_nop 1
	v_pk_add_f32 v[20:21], v[20:21], v[56:57] op_sel_hi:[1,0]
	v_or_b32_e32 v22, 3, v37
	v_mad_i64_i32 v[22:23], s[8:9], v22, s61, v[38:39]
	v_pk_add_f32 v[18:19], v[18:19], v[56:57] op_sel_hi:[1,0]
	global_store_dwordx4 v[22:23], v[18:21], off
	s_nop 1
	v_pk_add_f32 v[16:17], v[16:17], v[58:59] op_sel_hi:[1,0]
	v_or_b32_e32 v18, 4, v37
	v_mad_i64_i32 v[18:19], s[8:9], v18, s61, v[38:39]
	v_pk_add_f32 v[14:15], v[14:15], v[58:59] op_sel_hi:[1,0]
	global_store_dwordx4 v[18:19], v[14:17], off
	s_nop 1
	v_pk_add_f32 v[12:13], v[12:13], v[60:61] op_sel_hi:[1,0]
	v_or_b32_e32 v14, 5, v37
	v_mad_i64_i32 v[14:15], s[8:9], v14, s61, v[38:39]
	v_pk_add_f32 v[10:11], v[10:11], v[60:61] op_sel_hi:[1,0]
	global_store_dwordx4 v[14:15], v[10:13], off
	s_nop 1
	v_pk_add_f32 v[8:9], v[8:9], v[62:63] op_sel_hi:[1,0]
	v_or_b32_e32 v10, 6, v37
	v_mad_i64_i32 v[10:11], s[8:9], v10, s61, v[38:39]
	v_pk_add_f32 v[6:7], v[6:7], v[62:63] op_sel_hi:[1,0]
	global_store_dwordx4 v[10:11], v[6:9], off
	s_nop 1
	v_pk_add_f32 v[4:5], v[4:5], v[64:65] op_sel_hi:[1,0]
	v_or_b32_e32 v6, 7, v37
	v_mad_i64_i32 v[6:7], s[8:9], v6, s61, v[38:39]
	v_pk_add_f32 v[2:3], v[2:3], v[64:65] op_sel_hi:[1,0]
	global_store_dwordx4 v[6:7], v[2:5], off
	s_nop 1
	s_barrier
	s_cbranch_scc0 .LBB0_564
